# v15 + barrier release by polling the cross-XCD arrival counter TOP >= (gen+1)*nx: the last leader no longer bumps TOPGEN (one atomic hop less per barrier)
# speedup vs baseline: 1.0091x; 1.0091x over previous
.LBB0_60:
	s_or_b64 exec, exec, s[8:9]
	v_cvt_f32_u32_e32 v5, v3
	s_waitcnt vmcnt(0)
	v_readfirstlane_b32 s6, v4
	v_sub_u32_e32 v4, 0, v3
	v_rcp_iflag_f32_e32 v5, v5
	v_add_u32_e32 v6, s6, v2
	v_mul_f32_e32 v5, 0x4f7ffffe, v5
	v_cvt_u32_f32_e32 v5, v5
	v_mul_lo_u32 v2, v4, v5
	v_mul_hi_u32 v2, v5, v2
	v_add_u32_e32 v2, v5, v2
	v_mul_hi_u32 v2, v6, v2
	v_mul_lo_u32 v4, v2, v3
	v_sub_u32_e32 v4, v6, v4
	v_add_u32_e32 v5, 1, v2
	v_cmp_ge_u32_e32 vcc, v4, v3
	s_nop 1
	v_cndmask_b32_e32 v2, v2, v5, vcc
	v_sub_u32_e32 v5, v4, v3
	v_cndmask_b32_e32 v4, v4, v5, vcc
	v_add_u32_e32 v5, 1, v2
	v_cmp_ge_u32_e32 vcc, v4, v3
	v_add_u32_e32 v4, 1, v6
	s_nop 0
	v_cndmask_b32_e32 v2, v2, v5, vcc
	v_mul_lo_u32 v5, v3, v2
	v_add_u32_e32 v3, v5, v3
	v_cmp_ne_u32_e32 vcc, v4, v3
	s_and_saveexec_b64 s[6:7], vcc
	s_xor_b64 s[6:7], exec, s[6:7]
	s_cbranch_execz .LBB0_74
	s_waitcnt lgkmcnt(0)
	v_add_u32_e32 v252, 1, v2
	v_mul_lo_u32 v252, v252, v1
	v_mov_b32_e32 v1, 0x3400
	global_load_dword v1, v1, s[96:97] sc1
	s_add_u32 s10, s96, 0x3400
	s_addc_u32 s11, s97, 0
	s_waitcnt vmcnt(0)
	v_cmp_lt_u32_e32 vcc, v1, v252
	s_and_saveexec_b64 s[8:9], vcc
	s_cbranch_execz .LBB0_73
	s_mov_b32 s22, 1
	s_mov_b64 s[12:13], 0
	v_mov_b32_e32 v1, 0
	s_branch .LBB0_64

.LBB0_68:
	global_load_dword v3, v1, s[10:11] sc1
	s_add_i32 s22, s22, 1
	s_mov_b64 s[18:19], -1
	s_waitcnt vmcnt(0)
	v_cmp_ge_u32_e32 vcc, v3, v252
	s_orn2_b64 s[16:17], vcc, exec
	s_branch .LBB0_63

.LBB0_77:
	s_or_b64 exec, exec, s[8:9]
	v_cvt_f32_u32_e32 v4, v1
	s_waitcnt vmcnt(0)
	v_readfirstlane_b32 s6, v3
	s_add_u32 s8, s96, 0x3400
	s_addc_u32 s9, s97, 0
	v_rcp_iflag_f32_e32 v4, v4
	v_add_u32_e32 v2, s6, v2
	v_add_u32_e32 v5, 1, v2
	s_mov_b64 s[10:11], 0
	v_mul_f32_e32 v3, 0x4f7ffffe, v4
	v_cvt_u32_f32_e32 v3, v3
	v_sub_u32_e32 v4, 0, v1
	v_mul_lo_u32 v4, v4, v3
	v_mul_hi_u32 v4, v3, v4
	v_add_u32_e32 v3, v3, v4
	v_mul_hi_u32 v3, v2, v3
	v_mul_lo_u32 v4, v3, v1
	v_sub_u32_e32 v2, v2, v4
	v_add_u32_e32 v6, 1, v3
	v_cmp_ge_u32_e32 vcc, v2, v1
	v_sub_u32_e32 v4, v2, v1
	s_nop 0
	v_cndmask_b32_e32 v3, v3, v6, vcc
	v_cndmask_b32_e32 v2, v2, v4, vcc
	v_add_u32_e32 v4, 1, v3
	v_cmp_ge_u32_e32 vcc, v2, v1
	s_nop 1
	v_cndmask_b32_e32 v4, v3, v4, vcc
	v_mul_lo_u32 v2, v1, v4
	v_add_u32_e32 v1, v2, v1
	v_mov_b32_e32 v252, v1
	v_cmp_ne_u32_e32 vcc, v5, v1
	v_mov_b64_e32 v[2:3], s[8:9]
	s_and_saveexec_b64 s[6:7], vcc
	s_cbranch_execz .LBB0_89
	v_mov_b32_e32 v1, 0
	global_load_dword v2, v1, s[8:9] sc1
	s_mov_b64 s[14:15], 0
	s_waitcnt vmcnt(0)
	v_cmp_lt_u32_e32 vcc, v2, v252
	s_and_saveexec_b64 s[12:13], vcc
	s_cbranch_execz .LBB0_88
	s_add_u32 s10, s96, 0x200
	s_addc_u32 s11, s97, 0
	s_mov_b32 s24, 1
	s_branch .LBB0_81

.LBB0_85:
	global_load_dword v2, v1, s[8:9] sc1
	s_add_i32 s24, s24, 1
	s_mov_b64 s[18:19], -1
	s_waitcnt vmcnt(0)
	v_cmp_ge_u32_e32 vcc, v2, v252
	s_orn2_b64 s[22:23], vcc, exec
	s_branch .LBB0_80

.LBB0_491:
	s_or_b64 exec, exec, s[12:13]
	v_cvt_f32_u32_e32 v5, v3
	s_waitcnt vmcnt(0)
	v_readfirstlane_b32 s10, v4
	v_sub_u32_e32 v4, 0, v3
	v_rcp_iflag_f32_e32 v5, v5
	v_add_u32_e32 v6, s10, v2
	v_mul_f32_e32 v5, 0x4f7ffffe, v5
	v_cvt_u32_f32_e32 v5, v5
	v_mul_lo_u32 v2, v4, v5
	v_mul_hi_u32 v2, v5, v2
	v_add_u32_e32 v2, v5, v2
	v_mul_hi_u32 v2, v6, v2
	v_mul_lo_u32 v4, v2, v3
	v_sub_u32_e32 v4, v6, v4
	v_add_u32_e32 v5, 1, v2
	v_cmp_ge_u32_e32 vcc, v4, v3
	s_nop 1
	v_cndmask_b32_e32 v2, v2, v5, vcc
	v_sub_u32_e32 v5, v4, v3
	v_cndmask_b32_e32 v4, v4, v5, vcc
	v_add_u32_e32 v5, 1, v2
	v_cmp_ge_u32_e32 vcc, v4, v3
	v_add_u32_e32 v4, 1, v6
	s_nop 0
	v_cndmask_b32_e32 v2, v2, v5, vcc
	v_mul_lo_u32 v5, v3, v2
	v_add_u32_e32 v3, v5, v3
	v_cmp_ne_u32_e32 vcc, v4, v3
	s_and_saveexec_b64 s[10:11], vcc
	s_xor_b64 s[10:11], exec, s[10:11]
	s_cbranch_execz .LBB0_505
	s_waitcnt lgkmcnt(0)
	v_add_u32_e32 v252, 1, v2
	v_mul_lo_u32 v252, v252, v1
	v_mov_b32_e32 v1, 0x3400
	global_load_dword v1, v1, s[96:97] sc1
	s_add_u32 s14, s96, 0x3400
	s_addc_u32 s15, s97, 0
	s_waitcnt vmcnt(0)
	v_cmp_lt_u32_e32 vcc, v1, v252
	s_and_saveexec_b64 s[12:13], vcc
	s_cbranch_execz .LBB0_504
	s_mov_b32 s26, 1
	s_mov_b64 s[16:17], 0
	v_mov_b32_e32 v1, 0
	s_branch .LBB0_495

.LBB0_499:
	global_load_dword v3, v1, s[14:15] sc1
	s_add_i32 s26, s26, 1
	s_mov_b64 s[22:23], -1
	s_waitcnt vmcnt(0)
	v_cmp_ge_u32_e32 vcc, v3, v252
	s_orn2_b64 s[20:21], vcc, exec
	s_branch .LBB0_494

.LBB0_508:
	s_or_b64 exec, exec, s[12:13]
	v_cvt_f32_u32_e32 v4, v1
	s_waitcnt vmcnt(0)
	v_readfirstlane_b32 s10, v3
	s_add_u32 s12, s96, 0x3400
	s_addc_u32 s13, s97, 0
	v_rcp_iflag_f32_e32 v4, v4
	v_add_u32_e32 v2, s10, v2
	v_add_u32_e32 v5, 1, v2
	s_mov_b64 s[14:15], 0
	v_mul_f32_e32 v3, 0x4f7ffffe, v4
	v_cvt_u32_f32_e32 v3, v3
	v_sub_u32_e32 v4, 0, v1
	v_mul_lo_u32 v4, v4, v3
	v_mul_hi_u32 v4, v3, v4
	v_add_u32_e32 v3, v3, v4
	v_mul_hi_u32 v3, v2, v3
	v_mul_lo_u32 v4, v3, v1
	v_sub_u32_e32 v2, v2, v4
	v_add_u32_e32 v6, 1, v3
	v_cmp_ge_u32_e32 vcc, v2, v1
	v_sub_u32_e32 v4, v2, v1
	s_nop 0
	v_cndmask_b32_e32 v3, v3, v6, vcc
	v_cndmask_b32_e32 v2, v2, v4, vcc
	v_add_u32_e32 v4, 1, v3
	v_cmp_ge_u32_e32 vcc, v2, v1
	s_nop 1
	v_cndmask_b32_e32 v4, v3, v4, vcc
	v_mul_lo_u32 v2, v1, v4
	v_add_u32_e32 v1, v2, v1
	v_mov_b32_e32 v252, v1
	v_cmp_ne_u32_e32 vcc, v5, v1
	v_mov_b64_e32 v[2:3], s[12:13]
	s_and_saveexec_b64 s[10:11], vcc
	s_cbranch_execz .LBB0_520
	v_mov_b32_e32 v1, 0
	global_load_dword v2, v1, s[12:13] sc1
	s_mov_b64 s[18:19], 0
	s_waitcnt vmcnt(0)
	v_cmp_lt_u32_e32 vcc, v2, v252
	s_and_saveexec_b64 s[16:17], vcc
	s_cbranch_execz .LBB0_519
	s_add_u32 s14, s96, 0x200
	s_addc_u32 s15, s97, 0
	s_mov_b32 s30, 1
	s_branch .LBB0_512

.LBB0_516:
	global_load_dword v2, v1, s[12:13] sc1
	s_add_i32 s30, s30, 1
	s_mov_b64 s[22:23], -1
	s_waitcnt vmcnt(0)
	v_cmp_ge_u32_e32 vcc, v2, v252
	s_orn2_b64 s[26:27], vcc, exec
	s_branch .LBB0_511

.LBB0_641:
	s_or_b64 exec, exec, s[10:11]
	v_cvt_f32_u32_e32 v5, v3
	s_waitcnt vmcnt(0)
	v_readfirstlane_b32 s6, v4
	v_sub_u32_e32 v4, 0, v3
	v_rcp_iflag_f32_e32 v5, v5
	v_add_u32_e32 v6, s6, v2
	v_mul_f32_e32 v5, 0x4f7ffffe, v5
	v_cvt_u32_f32_e32 v5, v5
	v_mul_lo_u32 v2, v4, v5
	v_mul_hi_u32 v2, v5, v2
	v_add_u32_e32 v2, v5, v2
	v_mul_hi_u32 v2, v6, v2
	v_mul_lo_u32 v4, v2, v3
	v_sub_u32_e32 v4, v6, v4
	v_add_u32_e32 v5, 1, v2
	v_cmp_ge_u32_e32 vcc, v4, v3
	s_nop 1
	v_cndmask_b32_e32 v2, v2, v5, vcc
	v_sub_u32_e32 v5, v4, v3
	v_cndmask_b32_e32 v4, v4, v5, vcc
	v_add_u32_e32 v5, 1, v2
	v_cmp_ge_u32_e32 vcc, v4, v3
	v_add_u32_e32 v4, 1, v6
	s_nop 0
	v_cndmask_b32_e32 v2, v2, v5, vcc
	v_mul_lo_u32 v5, v3, v2
	v_add_u32_e32 v3, v5, v3
	v_cmp_ne_u32_e32 vcc, v4, v3
	s_and_saveexec_b64 s[6:7], vcc
	s_xor_b64 s[6:7], exec, s[6:7]
	s_cbranch_execz .LBB0_655
	s_waitcnt lgkmcnt(0)
	v_add_u32_e32 v252, 1, v2
	v_mul_lo_u32 v252, v252, v1
	v_mov_b32_e32 v1, 0x3400
	global_load_dword v1, v1, s[96:97] sc1
	s_add_u32 s12, s96, 0x3400
	s_addc_u32 s13, s97, 0
	s_waitcnt vmcnt(0)
	v_cmp_lt_u32_e32 vcc, v1, v252
	s_and_saveexec_b64 s[10:11], vcc
	s_cbranch_execz .LBB0_654
	s_mov_b32 s24, 1
	s_mov_b64 s[14:15], 0
	v_mov_b32_e32 v1, 0
	s_branch .LBB0_645

.LBB0_649:
	global_load_dword v3, v1, s[12:13] sc1
	s_add_i32 s24, s24, 1
	s_mov_b64 s[20:21], -1
	s_waitcnt vmcnt(0)
	v_cmp_ge_u32_e32 vcc, v3, v252
	s_orn2_b64 s[18:19], vcc, exec
	s_branch .LBB0_644

.LBB0_658:
	s_or_b64 exec, exec, s[10:11]
	v_cvt_f32_u32_e32 v4, v1
	s_waitcnt vmcnt(0)
	v_readfirstlane_b32 s6, v3
	s_add_u32 s10, s96, 0x3400
	s_addc_u32 s11, s97, 0
	v_rcp_iflag_f32_e32 v4, v4
	v_add_u32_e32 v2, s6, v2
	v_add_u32_e32 v5, 1, v2
	s_mov_b64 s[12:13], 0
	v_mul_f32_e32 v3, 0x4f7ffffe, v4
	v_cvt_u32_f32_e32 v3, v3
	v_sub_u32_e32 v4, 0, v1
	v_mul_lo_u32 v4, v4, v3
	v_mul_hi_u32 v4, v3, v4
	v_add_u32_e32 v3, v3, v4
	v_mul_hi_u32 v3, v2, v3
	v_mul_lo_u32 v4, v3, v1
	v_sub_u32_e32 v2, v2, v4
	v_add_u32_e32 v6, 1, v3
	v_cmp_ge_u32_e32 vcc, v2, v1
	v_sub_u32_e32 v4, v2, v1
	s_nop 0
	v_cndmask_b32_e32 v3, v3, v6, vcc
	v_cndmask_b32_e32 v2, v2, v4, vcc
	v_add_u32_e32 v4, 1, v3
	v_cmp_ge_u32_e32 vcc, v2, v1
	s_nop 1
	v_cndmask_b32_e32 v4, v3, v4, vcc
	v_mul_lo_u32 v2, v1, v4
	v_add_u32_e32 v1, v2, v1
	v_mov_b32_e32 v252, v1
	v_cmp_ne_u32_e32 vcc, v5, v1
	v_mov_b64_e32 v[2:3], s[10:11]
	s_and_saveexec_b64 s[6:7], vcc
	s_cbranch_execz .LBB0_670
	v_mov_b32_e32 v1, 0
	global_load_dword v2, v1, s[10:11] sc1
	s_mov_b64 s[16:17], 0
	s_waitcnt vmcnt(0)
	v_cmp_lt_u32_e32 vcc, v2, v252
	s_and_saveexec_b64 s[14:15], vcc
	s_cbranch_execz .LBB0_669
	s_add_u32 s12, s96, 0x200
	s_addc_u32 s13, s97, 0
	s_mov_b32 s26, 1
	s_branch .LBB0_662

.LBB0_666:
	global_load_dword v2, v1, s[10:11] sc1
	s_add_i32 s26, s26, 1
	s_mov_b64 s[20:21], -1
	s_waitcnt vmcnt(0)
	v_cmp_ge_u32_e32 vcc, v2, v252
	s_orn2_b64 s[24:25], vcc, exec
	s_branch .LBB0_661

.LBB0_895:
	s_or_b64 exec, exec, s[10:11]
	v_cvt_f32_u32_e32 v6, v4
	s_waitcnt vmcnt(0)
	v_readfirstlane_b32 s6, v5
	v_sub_u32_e32 v5, 0, v4
	v_rcp_iflag_f32_e32 v6, v6
	v_add_u32_e32 v7, s6, v3
	v_mul_f32_e32 v6, 0x4f7ffffe, v6
	v_cvt_u32_f32_e32 v6, v6
	v_mul_lo_u32 v3, v5, v6
	v_mul_hi_u32 v3, v6, v3
	v_add_u32_e32 v3, v6, v3
	v_mul_hi_u32 v3, v7, v3
	v_mul_lo_u32 v5, v3, v4
	v_sub_u32_e32 v5, v7, v5
	v_add_u32_e32 v6, 1, v3
	v_cmp_ge_u32_e32 vcc, v5, v4
	s_nop 1
	v_cndmask_b32_e32 v3, v3, v6, vcc
	v_sub_u32_e32 v6, v5, v4
	v_cndmask_b32_e32 v5, v5, v6, vcc
	v_add_u32_e32 v6, 1, v3
	v_cmp_ge_u32_e32 vcc, v5, v4
	v_add_u32_e32 v5, 1, v7
	s_nop 0
	v_cndmask_b32_e32 v3, v3, v6, vcc
	v_mul_lo_u32 v6, v4, v3
	v_add_u32_e32 v4, v6, v4
	v_cmp_ne_u32_e32 vcc, v5, v4
	s_and_saveexec_b64 s[6:7], vcc
	s_xor_b64 s[6:7], exec, s[6:7]
	s_cbranch_execz .LBB0_909
	s_waitcnt lgkmcnt(0)
	v_add_u32_e32 v252, 1, v3
	v_mul_lo_u32 v252, v252, v2
	v_mov_b32_e32 v2, 0x3400
	global_load_dword v2, v2, s[96:97] sc1
	s_add_u32 s12, s96, 0x3400
	s_addc_u32 s13, s97, 0
	s_waitcnt vmcnt(0)
	v_cmp_lt_u32_e32 vcc, v2, v252
	s_and_saveexec_b64 s[10:11], vcc
	s_cbranch_execz .LBB0_908
	s_mov_b32 s24, 1
	s_mov_b64 s[14:15], 0
	v_mov_b32_e32 v2, 0
	s_branch .LBB0_899

.LBB0_903:
	global_load_dword v4, v2, s[12:13] sc1
	s_add_i32 s24, s24, 1
	s_mov_b64 s[20:21], -1
	s_waitcnt vmcnt(0)
	v_cmp_ge_u32_e32 vcc, v4, v252
	s_orn2_b64 s[18:19], vcc, exec
	s_branch .LBB0_898

.LBB0_912:
	s_or_b64 exec, exec, s[10:11]
	v_cvt_f32_u32_e32 v5, v2
	s_waitcnt vmcnt(0)
	v_readfirstlane_b32 s6, v4
	s_add_u32 s10, s96, 0x3400
	s_addc_u32 s11, s97, 0
	v_rcp_iflag_f32_e32 v5, v5
	v_add_u32_e32 v3, s6, v3
	v_add_u32_e32 v6, 1, v3
	s_mov_b64 s[12:13], 0
	v_mul_f32_e32 v4, 0x4f7ffffe, v5
	v_cvt_u32_f32_e32 v4, v4
	v_sub_u32_e32 v5, 0, v2
	v_mul_lo_u32 v5, v5, v4
	v_mul_hi_u32 v5, v4, v5
	v_add_u32_e32 v4, v4, v5
	v_mul_hi_u32 v4, v3, v4
	v_mul_lo_u32 v5, v4, v2
	v_sub_u32_e32 v3, v3, v5
	v_add_u32_e32 v7, 1, v4
	v_cmp_ge_u32_e32 vcc, v3, v2
	v_sub_u32_e32 v5, v3, v2
	s_nop 0
	v_cndmask_b32_e32 v4, v4, v7, vcc
	v_cndmask_b32_e32 v3, v3, v5, vcc
	v_add_u32_e32 v5, 1, v4
	v_cmp_ge_u32_e32 vcc, v3, v2
	s_nop 1
	v_cndmask_b32_e32 v4, v4, v5, vcc
	v_mul_lo_u32 v3, v2, v4
	v_add_u32_e32 v2, v3, v2
	v_mov_b32_e32 v252, v2
	v_cmp_ne_u32_e32 vcc, v6, v2
	v_mov_b64_e32 v[2:3], s[10:11]
	s_and_saveexec_b64 s[6:7], vcc
	s_cbranch_execz .LBB0_924
	v_mov_b32_e32 v2, 0
	global_load_dword v3, v2, s[10:11] sc1
	s_mov_b64 s[16:17], 0
	s_waitcnt vmcnt(0)
	v_cmp_lt_u32_e32 vcc, v3, v252
	s_and_saveexec_b64 s[14:15], vcc
	s_cbranch_execz .LBB0_923
	s_add_u32 s12, s96, 0x200
	s_addc_u32 s13, s97, 0
	s_mov_b32 s26, 1
	s_branch .LBB0_916

.LBB0_920:
	global_load_dword v3, v2, s[10:11] sc1
	s_add_i32 s26, s26, 1
	s_mov_b64 s[20:21], -1
	s_waitcnt vmcnt(0)
	v_cmp_ge_u32_e32 vcc, v3, v252
	s_orn2_b64 s[24:25], vcc, exec
	s_branch .LBB0_915

.LBB0_952:
	s_or_b64 exec, exec, s[6:7]
	v_cvt_f32_u32_e32 v6, v4
	s_waitcnt vmcnt(0)
	v_readfirstlane_b32 s4, v5
	v_sub_u32_e32 v5, 0, v4
	v_rcp_iflag_f32_e32 v6, v6
	v_add_u32_e32 v7, s4, v3
	v_mul_f32_e32 v6, 0x4f7ffffe, v6
	v_cvt_u32_f32_e32 v6, v6
	v_mul_lo_u32 v3, v5, v6
	v_mul_hi_u32 v3, v6, v3
	v_add_u32_e32 v3, v6, v3
	v_mul_hi_u32 v3, v7, v3
	v_mul_lo_u32 v5, v3, v4
	v_sub_u32_e32 v5, v7, v5
	v_add_u32_e32 v6, 1, v3
	v_cmp_ge_u32_e32 vcc, v5, v4
	s_nop 1
	v_cndmask_b32_e32 v3, v3, v6, vcc
	v_sub_u32_e32 v6, v5, v4
	v_cndmask_b32_e32 v5, v5, v6, vcc
	v_add_u32_e32 v6, 1, v3
	v_cmp_ge_u32_e32 vcc, v5, v4
	v_add_u32_e32 v5, 1, v7
	s_nop 0
	v_cndmask_b32_e32 v3, v3, v6, vcc
	v_mul_lo_u32 v6, v4, v3
	v_add_u32_e32 v4, v6, v4
	v_cmp_ne_u32_e32 vcc, v5, v4
	s_and_saveexec_b64 s[4:5], vcc
	s_xor_b64 s[4:5], exec, s[4:5]
	s_cbranch_execz .LBB0_966
	s_waitcnt lgkmcnt(0)
	v_add_u32_e32 v252, 1, v3
	v_mul_lo_u32 v252, v252, v2
	v_mov_b32_e32 v2, 0x3400
	global_load_dword v2, v2, s[96:97] sc1
	s_add_u32 s12, s96, 0x3400
	s_addc_u32 s13, s97, 0
	s_waitcnt vmcnt(0)
	v_cmp_lt_u32_e32 vcc, v2, v252
	s_and_saveexec_b64 s[6:7], vcc
	s_cbranch_execz .LBB0_965
	s_mov_b32 s24, 1
	s_mov_b64 s[14:15], 0
	v_mov_b32_e32 v2, 0
	s_branch .LBB0_956

.LBB0_969:
	s_or_b64 exec, exec, s[6:7]
	v_cvt_f32_u32_e32 v5, v2
	s_waitcnt vmcnt(0)
	v_readfirstlane_b32 s4, v4
	s_add_u32 s6, s96, 0x3400
	s_addc_u32 s7, s97, 0
	v_rcp_iflag_f32_e32 v5, v5
	v_add_u32_e32 v3, s4, v3
	v_add_u32_e32 v6, 1, v3
	s_mov_b64 s[12:13], 0
	v_mul_f32_e32 v4, 0x4f7ffffe, v5
	v_cvt_u32_f32_e32 v4, v4
	v_sub_u32_e32 v5, 0, v2
	v_mul_lo_u32 v5, v5, v4
	v_mul_hi_u32 v5, v4, v5
	v_add_u32_e32 v4, v4, v5
	v_mul_hi_u32 v4, v3, v4
	v_mul_lo_u32 v5, v4, v2
	v_sub_u32_e32 v3, v3, v5
	v_add_u32_e32 v7, 1, v4
	v_cmp_ge_u32_e32 vcc, v3, v2
	v_sub_u32_e32 v5, v3, v2
	s_nop 0
	v_cndmask_b32_e32 v4, v4, v7, vcc
	v_cndmask_b32_e32 v3, v3, v5, vcc
	v_add_u32_e32 v5, 1, v4
	v_cmp_ge_u32_e32 vcc, v3, v2
	s_nop 1
	v_cndmask_b32_e32 v4, v4, v5, vcc
	v_mul_lo_u32 v3, v2, v4
	v_add_u32_e32 v2, v3, v2
	v_mov_b32_e32 v252, v2
	v_cmp_ne_u32_e32 vcc, v6, v2
	v_mov_b64_e32 v[2:3], s[6:7]
	s_and_saveexec_b64 s[4:5], vcc
	s_cbranch_execz .LBB0_981
	v_mov_b32_e32 v2, 0
	global_load_dword v3, v2, s[6:7] sc1
	s_mov_b64 s[16:17], 0
	s_waitcnt vmcnt(0)
	v_cmp_lt_u32_e32 vcc, v3, v252
	s_and_saveexec_b64 s[14:15], vcc
	s_cbranch_execz .LBB0_980
	s_add_u32 s12, s96, 0x200
	s_addc_u32 s13, s97, 0
	s_mov_b32 s26, 1
	s_branch .LBB0_973

.LBB0_977:
	global_load_dword v3, v2, s[6:7] sc1
	s_add_i32 s26, s26, 1
	s_mov_b64 s[20:21], -1
	s_waitcnt vmcnt(0)
	v_cmp_ge_u32_e32 vcc, v3, v252
	s_orn2_b64 s[24:25], vcc, exec
	s_branch .LBB0_972

.LBB0_1037:
	s_or_b64 exec, exec, s[10:11]
	v_cvt_f32_u32_e32 v6, v4
	s_waitcnt vmcnt(0)
	v_readfirstlane_b32 s8, v5
	v_sub_u32_e32 v5, 0, v4
	v_rcp_iflag_f32_e32 v6, v6
	v_add_u32_e32 v7, s8, v3
	v_mul_f32_e32 v6, 0x4f7ffffe, v6
	v_cvt_u32_f32_e32 v6, v6
	v_mul_lo_u32 v3, v5, v6
	v_mul_hi_u32 v3, v6, v3
	v_add_u32_e32 v3, v6, v3
	v_mul_hi_u32 v3, v7, v3
	v_mul_lo_u32 v5, v3, v4
	v_sub_u32_e32 v5, v7, v5
	v_add_u32_e32 v6, 1, v3
	v_cmp_ge_u32_e32 vcc, v5, v4
	s_nop 1
	v_cndmask_b32_e32 v3, v3, v6, vcc
	v_sub_u32_e32 v6, v5, v4
	v_cndmask_b32_e32 v5, v5, v6, vcc
	v_add_u32_e32 v6, 1, v3
	v_cmp_ge_u32_e32 vcc, v5, v4
	v_add_u32_e32 v5, 1, v7
	s_nop 0
	v_cndmask_b32_e32 v3, v3, v6, vcc
	v_mul_lo_u32 v6, v4, v3
	v_add_u32_e32 v4, v6, v4
	v_cmp_ne_u32_e32 vcc, v5, v4
	s_and_saveexec_b64 s[8:9], vcc
	s_xor_b64 s[8:9], exec, s[8:9]
	s_cbranch_execz .LBB0_1051
	s_waitcnt lgkmcnt(0)
	v_add_u32_e32 v252, 1, v3
	v_mul_lo_u32 v252, v252, v2
	v_mov_b32_e32 v2, 0x3400
	global_load_dword v2, v2, s[96:97] sc1
	s_add_u32 s12, s96, 0x3400
	s_addc_u32 s13, s97, 0
	s_waitcnt vmcnt(0)
	v_cmp_lt_u32_e32 vcc, v2, v252
	s_and_saveexec_b64 s[10:11], vcc
	s_cbranch_execz .LBB0_1050
	s_mov_b32 s24, 1
	s_mov_b64 s[14:15], 0
	v_mov_b32_e32 v2, 0
	s_branch .LBB0_1041

.LBB0_1054:
	s_or_b64 exec, exec, s[10:11]
	v_cvt_f32_u32_e32 v5, v2
	s_waitcnt vmcnt(0)
	v_readfirstlane_b32 s8, v4
	s_add_u32 s10, s96, 0x3400
	s_addc_u32 s11, s97, 0
	v_rcp_iflag_f32_e32 v5, v5
	v_add_u32_e32 v3, s8, v3
	v_add_u32_e32 v6, 1, v3
	s_mov_b64 s[12:13], 0
	v_mul_f32_e32 v4, 0x4f7ffffe, v5
	v_cvt_u32_f32_e32 v4, v4
	v_sub_u32_e32 v5, 0, v2
	v_mul_lo_u32 v5, v5, v4
	v_mul_hi_u32 v5, v4, v5
	v_add_u32_e32 v4, v4, v5
	v_mul_hi_u32 v4, v3, v4
	v_mul_lo_u32 v5, v4, v2
	v_sub_u32_e32 v3, v3, v5
	v_add_u32_e32 v7, 1, v4
	v_cmp_ge_u32_e32 vcc, v3, v2
	v_sub_u32_e32 v5, v3, v2
	s_nop 0
	v_cndmask_b32_e32 v4, v4, v7, vcc
	v_cndmask_b32_e32 v3, v3, v5, vcc
	v_add_u32_e32 v5, 1, v4
	v_cmp_ge_u32_e32 vcc, v3, v2
	s_nop 1
	v_cndmask_b32_e32 v4, v4, v5, vcc
	v_mul_lo_u32 v3, v2, v4
	v_add_u32_e32 v2, v3, v2
	v_mov_b32_e32 v252, v2
	v_cmp_ne_u32_e32 vcc, v6, v2
	v_mov_b64_e32 v[2:3], s[10:11]
	s_and_saveexec_b64 s[8:9], vcc
	s_cbranch_execz .LBB0_1066
	v_mov_b32_e32 v2, 0
	global_load_dword v3, v2, s[10:11] sc1
	s_mov_b64 s[16:17], 0
	s_waitcnt vmcnt(0)
	v_cmp_lt_u32_e32 vcc, v3, v252
	s_and_saveexec_b64 s[14:15], vcc
	s_cbranch_execz .LBB0_1065
	s_add_u32 s12, s96, 0x200
	s_addc_u32 s13, s97, 0
	s_mov_b32 s26, 1
	s_branch .LBB0_1058

.LBB0_1166:
	s_or_b64 exec, exec, s[16:17]
	v_cvt_f32_u32_e32 v6, v4
	s_waitcnt vmcnt(0)
	v_readfirstlane_b32 s6, v5
	v_sub_u32_e32 v5, 0, v4
	v_rcp_iflag_f32_e32 v6, v6
	v_add_u32_e32 v7, s6, v3
	v_mul_f32_e32 v6, 0x4f7ffffe, v6
	v_cvt_u32_f32_e32 v6, v6
	v_mul_lo_u32 v3, v5, v6
	v_mul_hi_u32 v3, v6, v3
	v_add_u32_e32 v3, v6, v3
	v_mul_hi_u32 v3, v7, v3
	v_mul_lo_u32 v5, v3, v4
	v_sub_u32_e32 v5, v7, v5
	v_add_u32_e32 v6, 1, v3
	v_cmp_ge_u32_e32 vcc, v5, v4
	s_nop 1
	v_cndmask_b32_e32 v3, v3, v6, vcc
	v_sub_u32_e32 v6, v5, v4
	v_cndmask_b32_e32 v5, v5, v6, vcc
	v_add_u32_e32 v6, 1, v3
	v_cmp_ge_u32_e32 vcc, v5, v4
	v_add_u32_e32 v5, 1, v7
	s_nop 0
	v_cndmask_b32_e32 v3, v3, v6, vcc
	v_mul_lo_u32 v6, v4, v3
	v_add_u32_e32 v4, v6, v4
	v_cmp_ne_u32_e32 vcc, v5, v4
	s_and_saveexec_b64 s[6:7], vcc
	s_xor_b64 s[6:7], exec, s[6:7]
	s_cbranch_execz .LBB0_1180
	s_waitcnt lgkmcnt(0)
	v_add_u32_e32 v252, 1, v3
	v_mul_lo_u32 v252, v252, v2
	v_mov_b32_e32 v2, 0x3400
	global_load_dword v2, v2, s[96:97] sc1
	s_add_u32 s18, s96, 0x3400
	s_addc_u32 s19, s97, 0
	s_waitcnt vmcnt(0)
	v_cmp_lt_u32_e32 vcc, v2, v252
	s_and_saveexec_b64 s[16:17], vcc
	s_cbranch_execz .LBB0_1179
	s_mov_b32 s30, 1
	s_mov_b64 s[20:21], 0
	v_mov_b32_e32 v2, 0
	s_branch .LBB0_1170

.LBB0_1174:
	global_load_dword v4, v2, s[18:19] sc1
	s_add_i32 s30, s30, 1
	s_mov_b64 s[26:27], -1
	s_waitcnt vmcnt(0)
	v_cmp_ge_u32_e32 vcc, v4, v252
	s_orn2_b64 s[24:25], vcc, exec
	s_branch .LBB0_1169

.LBB0_1183:
	s_or_b64 exec, exec, s[16:17]
	v_cvt_f32_u32_e32 v5, v2
	s_waitcnt vmcnt(0)
	v_readfirstlane_b32 s6, v4
	s_add_u32 s16, s96, 0x3400
	s_addc_u32 s17, s97, 0
	v_rcp_iflag_f32_e32 v5, v5
	v_add_u32_e32 v3, s6, v3
	v_add_u32_e32 v6, 1, v3
	s_mov_b64 s[18:19], 0
	v_mul_f32_e32 v4, 0x4f7ffffe, v5
	v_cvt_u32_f32_e32 v4, v4
	v_sub_u32_e32 v5, 0, v2
	v_mul_lo_u32 v5, v5, v4
	v_mul_hi_u32 v5, v4, v5
	v_add_u32_e32 v4, v4, v5
	v_mul_hi_u32 v4, v3, v4
	v_mul_lo_u32 v5, v4, v2
	v_sub_u32_e32 v3, v3, v5
	v_add_u32_e32 v7, 1, v4
	v_cmp_ge_u32_e32 vcc, v3, v2
	v_sub_u32_e32 v5, v3, v2
	s_nop 0
	v_cndmask_b32_e32 v4, v4, v7, vcc
	v_cndmask_b32_e32 v3, v3, v5, vcc
	v_add_u32_e32 v5, 1, v4
	v_cmp_ge_u32_e32 vcc, v3, v2
	s_nop 1
	v_cndmask_b32_e32 v4, v4, v5, vcc
	v_mul_lo_u32 v3, v2, v4
	v_add_u32_e32 v2, v3, v2
	v_mov_b32_e32 v252, v2
	v_cmp_ne_u32_e32 vcc, v6, v2
	v_mov_b64_e32 v[2:3], s[16:17]
	s_and_saveexec_b64 s[6:7], vcc
	s_cbranch_execz .LBB0_1195
	v_mov_b32_e32 v2, 0
	global_load_dword v3, v2, s[16:17] sc1
	s_mov_b64 s[22:23], 0
	s_waitcnt vmcnt(0)
	v_cmp_lt_u32_e32 vcc, v3, v252
	s_and_saveexec_b64 s[20:21], vcc
	s_cbranch_execz .LBB0_1194
	s_add_u32 s18, s96, 0x200
	s_addc_u32 s19, s97, 0
	s_mov_b32 s34, 1
	s_branch .LBB0_1187

.LBB0_1191:
	global_load_dword v3, v2, s[16:17] sc1
	s_add_i32 s34, s34, 1
	s_mov_b64 s[26:27], -1
	s_waitcnt vmcnt(0)
	v_cmp_ge_u32_e32 vcc, v3, v252
	s_orn2_b64 s[30:31], vcc, exec
	s_branch .LBB0_1186

.LBB0_1241:
	s_or_b64 exec, exec, s[18:19]
	v_cvt_f32_u32_e32 v6, v4
	s_waitcnt vmcnt(0)
	v_readfirstlane_b32 s16, v5
	v_sub_u32_e32 v5, 0, v4
	v_rcp_iflag_f32_e32 v6, v6
	v_add_u32_e32 v7, s16, v3
	v_mul_f32_e32 v6, 0x4f7ffffe, v6
	v_cvt_u32_f32_e32 v6, v6
	v_mul_lo_u32 v3, v5, v6
	v_mul_hi_u32 v3, v6, v3
	v_add_u32_e32 v3, v6, v3
	v_mul_hi_u32 v3, v7, v3
	v_mul_lo_u32 v5, v3, v4
	v_sub_u32_e32 v5, v7, v5
	v_add_u32_e32 v6, 1, v3
	v_cmp_ge_u32_e32 vcc, v5, v4
	s_nop 1
	v_cndmask_b32_e32 v3, v3, v6, vcc
	v_sub_u32_e32 v6, v5, v4
	v_cndmask_b32_e32 v5, v5, v6, vcc
	v_add_u32_e32 v6, 1, v3
	v_cmp_ge_u32_e32 vcc, v5, v4
	v_add_u32_e32 v5, 1, v7
	s_nop 0
	v_cndmask_b32_e32 v3, v3, v6, vcc
	v_mul_lo_u32 v6, v4, v3
	v_add_u32_e32 v4, v6, v4
	v_cmp_ne_u32_e32 vcc, v5, v4
	s_and_saveexec_b64 s[16:17], vcc
	s_xor_b64 s[16:17], exec, s[16:17]
	s_cbranch_execz .LBB0_1255
	s_waitcnt lgkmcnt(0)
	v_add_u32_e32 v252, 1, v3
	v_mul_lo_u32 v252, v252, v2
	v_mov_b32_e32 v2, 0x3400
	global_load_dword v2, v2, s[96:97] sc1
	s_add_u32 s20, s96, 0x3400
	s_addc_u32 s21, s97, 0
	s_waitcnt vmcnt(0)
	v_cmp_lt_u32_e32 vcc, v2, v252
	s_and_saveexec_b64 s[18:19], vcc
	s_cbranch_execz .LBB0_1254
	s_mov_b32 s34, 1
	s_mov_b64 s[22:23], 0
	v_mov_b32_e32 v2, 0
	s_branch .LBB0_1245

.LBB0_1249:
	global_load_dword v4, v2, s[20:21] sc1
	s_add_i32 s34, s34, 1
	s_mov_b64 s[28:29], -1
	s_waitcnt vmcnt(0)
	v_cmp_ge_u32_e32 vcc, v4, v252
	s_orn2_b64 s[26:27], vcc, exec
	s_branch .LBB0_1244

.LBB0_1258:
	s_or_b64 exec, exec, s[18:19]
	v_cvt_f32_u32_e32 v5, v2
	s_waitcnt vmcnt(0)
	v_readfirstlane_b32 s16, v4
	s_add_u32 s18, s96, 0x3400
	s_addc_u32 s19, s97, 0
	v_rcp_iflag_f32_e32 v5, v5
	v_add_u32_e32 v3, s16, v3
	v_add_u32_e32 v6, 1, v3
	s_mov_b64 s[20:21], 0
	v_mul_f32_e32 v4, 0x4f7ffffe, v5
	v_cvt_u32_f32_e32 v4, v4
	v_sub_u32_e32 v5, 0, v2
	v_mul_lo_u32 v5, v5, v4
	v_mul_hi_u32 v5, v4, v5
	v_add_u32_e32 v4, v4, v5
	v_mul_hi_u32 v4, v3, v4
	v_mul_lo_u32 v5, v4, v2
	v_sub_u32_e32 v3, v3, v5
	v_add_u32_e32 v7, 1, v4
	v_cmp_ge_u32_e32 vcc, v3, v2
	v_sub_u32_e32 v5, v3, v2
	s_nop 0
	v_cndmask_b32_e32 v4, v4, v7, vcc
	v_cndmask_b32_e32 v3, v3, v5, vcc
	v_add_u32_e32 v5, 1, v4
	v_cmp_ge_u32_e32 vcc, v3, v2
	s_nop 1
	v_cndmask_b32_e32 v4, v4, v5, vcc
	v_mul_lo_u32 v3, v2, v4
	v_add_u32_e32 v2, v3, v2
	v_mov_b32_e32 v252, v2
	v_cmp_ne_u32_e32 vcc, v6, v2
	v_mov_b64_e32 v[2:3], s[18:19]
	s_and_saveexec_b64 s[16:17], vcc
	s_cbranch_execz .LBB0_1270
	v_mov_b32_e32 v2, 0
	global_load_dword v3, v2, s[18:19] sc1
	s_mov_b64 s[24:25], 0
	s_waitcnt vmcnt(0)
	v_cmp_lt_u32_e32 vcc, v3, v252
	s_and_saveexec_b64 s[22:23], vcc
	s_cbranch_execz .LBB0_1269
	s_add_u32 s20, s96, 0x200
	s_addc_u32 s21, s97, 0
	s_mov_b32 s36, 1
	s_branch .LBB0_1262

.LBB0_1266:
	global_load_dword v3, v2, s[18:19] sc1
	s_add_i32 s36, s36, 1
	s_mov_b64 s[28:29], -1
	s_waitcnt vmcnt(0)
	v_cmp_ge_u32_e32 vcc, v3, v252
	s_orn2_b64 s[34:35], vcc, exec
	s_branch .LBB0_1261

.LBB0_1334:
	s_or_b64 exec, exec, s[16:17]
	v_cvt_f32_u32_e32 v6, v4
	s_waitcnt vmcnt(0)
	v_readfirstlane_b32 s14, v5
	v_sub_u32_e32 v5, 0, v4
	v_rcp_iflag_f32_e32 v6, v6
	v_add_u32_e32 v7, s14, v3
	v_mul_f32_e32 v6, 0x4f7ffffe, v6
	v_cvt_u32_f32_e32 v6, v6
	v_mul_lo_u32 v3, v5, v6
	v_mul_hi_u32 v3, v6, v3
	v_add_u32_e32 v3, v6, v3
	v_mul_hi_u32 v3, v7, v3
	v_mul_lo_u32 v5, v3, v4
	v_sub_u32_e32 v5, v7, v5
	v_add_u32_e32 v6, 1, v3
	v_cmp_ge_u32_e32 vcc, v5, v4
	s_nop 1
	v_cndmask_b32_e32 v3, v3, v6, vcc
	v_sub_u32_e32 v6, v5, v4
	v_cndmask_b32_e32 v5, v5, v6, vcc
	v_add_u32_e32 v6, 1, v3
	v_cmp_ge_u32_e32 vcc, v5, v4
	v_add_u32_e32 v5, 1, v7
	s_nop 0
	v_cndmask_b32_e32 v3, v3, v6, vcc
	v_mul_lo_u32 v6, v4, v3
	v_add_u32_e32 v4, v6, v4
	v_cmp_ne_u32_e32 vcc, v5, v4
	s_and_saveexec_b64 s[14:15], vcc
	s_xor_b64 s[14:15], exec, s[14:15]
	s_cbranch_execz .LBB0_1348
	s_waitcnt lgkmcnt(0)
	v_add_u32_e32 v252, 1, v3
	v_mul_lo_u32 v252, v252, v2
	v_mov_b32_e32 v2, 0x3400
	global_load_dword v2, v2, s[96:97] sc1
	s_add_u32 s20, s96, 0x3400
	s_addc_u32 s21, s97, 0
	s_waitcnt vmcnt(0)
	v_cmp_lt_u32_e32 vcc, v2, v252
	s_and_saveexec_b64 s[16:17], vcc
	s_cbranch_execz .LBB0_1347
	s_mov_b32 s34, 1
	s_mov_b64 s[22:23], 0
	v_mov_b32_e32 v2, 0
	s_branch .LBB0_1338

.LBB0_1351:
	s_or_b64 exec, exec, s[16:17]
	v_cvt_f32_u32_e32 v5, v2
	s_waitcnt vmcnt(0)
	v_readfirstlane_b32 s14, v4
	s_add_u32 s16, s96, 0x3400
	s_addc_u32 s17, s97, 0
	v_rcp_iflag_f32_e32 v5, v5
	v_add_u32_e32 v3, s14, v3
	v_add_u32_e32 v6, 1, v3
	s_mov_b64 s[20:21], 0
	v_mul_f32_e32 v4, 0x4f7ffffe, v5
	v_cvt_u32_f32_e32 v4, v4
	v_sub_u32_e32 v5, 0, v2
	v_mul_lo_u32 v5, v5, v4
	v_mul_hi_u32 v5, v4, v5
	v_add_u32_e32 v4, v4, v5
	v_mul_hi_u32 v4, v3, v4
	v_mul_lo_u32 v5, v4, v2
	v_sub_u32_e32 v3, v3, v5
	v_add_u32_e32 v7, 1, v4
	v_cmp_ge_u32_e32 vcc, v3, v2
	v_sub_u32_e32 v5, v3, v2
	s_nop 0
	v_cndmask_b32_e32 v4, v4, v7, vcc
	v_cndmask_b32_e32 v3, v3, v5, vcc
	v_add_u32_e32 v5, 1, v4
	v_cmp_ge_u32_e32 vcc, v3, v2
	s_nop 1
	v_cndmask_b32_e32 v4, v4, v5, vcc
	v_mul_lo_u32 v3, v2, v4
	v_add_u32_e32 v2, v3, v2
	v_mov_b32_e32 v252, v2
	v_cmp_ne_u32_e32 vcc, v6, v2
	v_mov_b64_e32 v[2:3], s[16:17]
	s_and_saveexec_b64 s[14:15], vcc
	s_cbranch_execz .LBB0_1363
	v_mov_b32_e32 v2, 0
	global_load_dword v3, v2, s[16:17] sc1
	s_mov_b64 s[24:25], 0
	s_waitcnt vmcnt(0)
	v_cmp_lt_u32_e32 vcc, v3, v252
	s_and_saveexec_b64 s[22:23], vcc
	s_cbranch_execz .LBB0_1362
	s_add_u32 s20, s96, 0x200
	s_addc_u32 s21, s97, 0
	s_mov_b32 s36, 1
	s_branch .LBB0_1355

.LBB0_1359:
	global_load_dword v3, v2, s[16:17] sc1
	s_add_i32 s36, s36, 1
	s_mov_b64 s[28:29], -1
	s_waitcnt vmcnt(0)
	v_cmp_ge_u32_e32 vcc, v3, v252
	s_orn2_b64 s[34:35], vcc, exec
	s_branch .LBB0_1354

.LBB0_1413:
	s_or_b64 exec, exec, s[8:9]
	v_cvt_f32_u32_e32 v6, v4
	s_waitcnt vmcnt(0)
	v_readfirstlane_b32 s6, v5
	v_sub_u32_e32 v5, 0, v4
	v_rcp_iflag_f32_e32 v6, v6
	v_add_u32_e32 v7, s6, v3
	v_mul_f32_e32 v6, 0x4f7ffffe, v6
	v_cvt_u32_f32_e32 v6, v6
	v_mul_lo_u32 v3, v5, v6
	v_mul_hi_u32 v3, v6, v3
	v_add_u32_e32 v3, v6, v3
	v_mul_hi_u32 v3, v7, v3
	v_mul_lo_u32 v5, v3, v4
	v_sub_u32_e32 v5, v7, v5
	v_add_u32_e32 v6, 1, v3
	v_cmp_ge_u32_e32 vcc, v5, v4
	s_nop 1
	v_cndmask_b32_e32 v3, v3, v6, vcc
	v_sub_u32_e32 v6, v5, v4
	v_cndmask_b32_e32 v5, v5, v6, vcc
	v_add_u32_e32 v6, 1, v3
	v_cmp_ge_u32_e32 vcc, v5, v4
	v_add_u32_e32 v5, 1, v7
	s_nop 0
	v_cndmask_b32_e32 v3, v3, v6, vcc
	v_mul_lo_u32 v6, v4, v3
	v_add_u32_e32 v4, v6, v4
	v_cmp_ne_u32_e32 vcc, v5, v4
	s_and_saveexec_b64 s[6:7], vcc
	s_xor_b64 s[6:7], exec, s[6:7]
	s_cbranch_execz .LBB0_1427
	s_waitcnt lgkmcnt(0)
	v_add_u32_e32 v252, 1, v3
	v_mul_lo_u32 v252, v252, v2
	v_mov_b32_e32 v2, 0x3400
	global_load_dword v2, v2, s[96:97] sc1
	s_add_u32 s10, s96, 0x3400
	s_addc_u32 s11, s97, 0
	s_waitcnt vmcnt(0)
	v_cmp_lt_u32_e32 vcc, v2, v252
	s_and_saveexec_b64 s[8:9], vcc
	s_cbranch_execz .LBB0_1426
	s_mov_b32 s22, 1
	s_mov_b64 s[12:13], 0
	v_mov_b32_e32 v2, 0
	s_branch .LBB0_1417

.LBB0_1421:
	global_load_dword v4, v2, s[10:11] sc1
	s_add_i32 s22, s22, 1
	s_mov_b64 s[18:19], -1
	s_waitcnt vmcnt(0)
	v_cmp_ge_u32_e32 vcc, v4, v252
	s_orn2_b64 s[16:17], vcc, exec
	s_branch .LBB0_1416

.LBB0_1430:
	s_or_b64 exec, exec, s[8:9]
	v_cvt_f32_u32_e32 v5, v2
	s_waitcnt vmcnt(0)
	v_readfirstlane_b32 s6, v4
	s_add_u32 s8, s96, 0x3400
	s_addc_u32 s9, s97, 0
	v_rcp_iflag_f32_e32 v5, v5
	v_add_u32_e32 v3, s6, v3
	v_add_u32_e32 v6, 1, v3
	s_mov_b64 s[10:11], 0
	v_mul_f32_e32 v4, 0x4f7ffffe, v5
	v_cvt_u32_f32_e32 v4, v4
	v_sub_u32_e32 v5, 0, v2
	v_mul_lo_u32 v5, v5, v4
	v_mul_hi_u32 v5, v4, v5
	v_add_u32_e32 v4, v4, v5
	v_mul_hi_u32 v4, v3, v4
	v_mul_lo_u32 v5, v4, v2
	v_sub_u32_e32 v3, v3, v5
	v_add_u32_e32 v7, 1, v4
	v_cmp_ge_u32_e32 vcc, v3, v2
	v_sub_u32_e32 v5, v3, v2
	s_nop 0
	v_cndmask_b32_e32 v4, v4, v7, vcc
	v_cndmask_b32_e32 v3, v3, v5, vcc
	v_add_u32_e32 v5, 1, v4
	v_cmp_ge_u32_e32 vcc, v3, v2
	s_nop 1
	v_cndmask_b32_e32 v4, v4, v5, vcc
	v_mul_lo_u32 v3, v2, v4
	v_add_u32_e32 v2, v3, v2
	v_mov_b32_e32 v252, v2
	v_cmp_ne_u32_e32 vcc, v6, v2
	v_mov_b64_e32 v[2:3], s[8:9]
	s_and_saveexec_b64 s[6:7], vcc
	s_cbranch_execz .LBB0_1442
	v_mov_b32_e32 v2, 0
	global_load_dword v3, v2, s[8:9] sc1
	s_mov_b64 s[14:15], 0
	s_waitcnt vmcnt(0)
	v_cmp_lt_u32_e32 vcc, v3, v252
	s_and_saveexec_b64 s[12:13], vcc
	s_cbranch_execz .LBB0_1441
	s_add_u32 s10, s96, 0x200
	s_addc_u32 s11, s97, 0
	s_mov_b32 s24, 1
	s_branch .LBB0_1434

.LBB0_1438:
	global_load_dword v3, v2, s[8:9] sc1
	s_add_i32 s24, s24, 1
	s_mov_b64 s[18:19], -1
	s_waitcnt vmcnt(0)
	v_cmp_ge_u32_e32 vcc, v3, v252
	s_orn2_b64 s[22:23], vcc, exec
	s_branch .LBB0_1433

	.amdhsa_kernel _Z6mk_fwd4Args
		.amdhsa_group_segment_fixed_size 0
		.amdhsa_private_segment_fixed_size 0
		.amdhsa_kernarg_size 440
		.amdhsa_user_sgpr_count 2
		.amdhsa_user_sgpr_dispatch_ptr 0
		.amdhsa_user_sgpr_queue_ptr 0
		.amdhsa_user_sgpr_kernarg_segment_ptr 1
		.amdhsa_user_sgpr_dispatch_id 0
		.amdhsa_user_sgpr_kernarg_preload_length 0
		.amdhsa_user_sgpr_kernarg_preload_offset 0
		.amdhsa_user_sgpr_private_segment_size 0
		.amdhsa_uses_dynamic_stack 0
		.amdhsa_enable_private_segment 0
		.amdhsa_system_sgpr_workgroup_id_x 1
		.amdhsa_system_sgpr_workgroup_id_y 0
		.amdhsa_system_sgpr_workgroup_id_z 0
		.amdhsa_system_sgpr_workgroup_info 0
		.amdhsa_system_vgpr_workitem_id 0
		.amdhsa_next_free_vgpr 256
		.amdhsa_next_free_sgpr 98
		.amdhsa_accum_offset 256
		.amdhsa_reserve_vcc 1
		.amdhsa_float_round_mode_32 0
		.amdhsa_float_round_mode_16_64 0
		.amdhsa_float_denorm_mode_32 3
		.amdhsa_float_denorm_mode_16_64 3
		.amdhsa_dx10_clamp 1
		.amdhsa_ieee_mode 1
		.amdhsa_fp16_overflow 0
		.amdhsa_tg_split 0
		.amdhsa_exception_fp_ieee_invalid_op 0
		.amdhsa_exception_fp_denorm_src 0
		.amdhsa_exception_fp_ieee_div_zero 0
		.amdhsa_exception_fp_ieee_overflow 0
		.amdhsa_exception_fp_ieee_underflow 0
		.amdhsa_exception_fp_ieee_inexact 0
		.amdhsa_exception_int_div_zero 0
	.end_amdhsa_kernel

amdhsa.kernels:
  - .agpr_count:     0
    .args:
      - .offset:         0
        .size:           184
        .value_kind:     by_value
      - .offset:         184
        .size:           4
        .value_kind:     hidden_block_count_x
      - .offset:         188
        .size:           4
        .value_kind:     hidden_block_count_y
      - .offset:         192
        .size:           4
        .value_kind:     hidden_block_count_z
      - .offset:         196
        .size:           2
        .value_kind:     hidden_group_size_x
      - .offset:         198
        .size:           2
        .value_kind:     hidden_group_size_y
      - .offset:         200
        .size:           2
        .value_kind:     hidden_group_size_z
      - .offset:         202
        .size:           2
        .value_kind:     hidden_remainder_x
      - .offset:         204
        .size:           2
        .value_kind:     hidden_remainder_y
      - .offset:         206
        .size:           2
        .value_kind:     hidden_remainder_z
      - .offset:         224
        .size:           8
        .value_kind:     hidden_global_offset_x
      - .offset:         232
        .size:           8
        .value_kind:     hidden_global_offset_y
      - .offset:         240
        .size:           8
        .value_kind:     hidden_global_offset_z
      - .offset:         248
        .size:           2
        .value_kind:     hidden_grid_dims
      - .offset:         304
        .size:           4
        .value_kind:     hidden_dynamic_lds_size
    .group_segment_fixed_size: 0
    .kernarg_segment_align: 8
    .kernarg_segment_size: 440
    .language:       OpenCL C
    .language_version:
      - 2
      - 0
    .max_flat_workgroup_size: 512
    .name:           _Z6mk_fwd4Args
    .private_segment_fixed_size: 0
    .sgpr_count:     104
    .sgpr_spill_count: 75
    .symbol:         _Z6mk_fwd4Args.kd
    .uniform_work_group_size: 1
    .uses_dynamic_stack: false
    .vgpr_count:     256
    .vgpr_spill_count: 0
    .wavefront_size: 64
